# w4 + loop-edge edits: attention key-loop back edge jumps straight to the steady-state wait, seven hipcc VALU wave-uniform branch tests replaced by s_andn2
# baseline (speedup 1.0000x reference)
.LBB0_37:
	s_andn2_b64 s[4:5], exec, s[44:45]
	s_andn2_b64 vcc, exec, s[44:45]
	s_cbranch_vccnz .LBB0_39
	v_lshl_add_u64 v[4:5], v[0:1], 0, v[40:41]
	v_add_co_u32_e32 v4, vcc, 0x4000, v4
	s_nop 1
	v_addc_co_u32_e32 v5, vcc, 0, v5, vcc
	global_load_dword v3, v[4:5], off nt

.LBB0_447:
	v_add_u32_e32 v0, s23, v225
	ds_read_b128 v[148:151], v0
	ds_read_b128 v[152:155], v0 offset:1024
	ds_read_b128 v[156:159], v0 offset:2048
	ds_read_b128 v[160:163], v0 offset:3072
	v_add_u32_e32 v0, s50, v225
	ds_read_b128 v[132:135], v0
	ds_read_b128 v[136:139], v0 offset:1024
	ds_read_b128 v[140:143], v0 offset:2048
	ds_read_b128 v[144:147], v0 offset:3072
	v_lshl_add_u64 v[2:3], v[216:217], 0, s[28:29]
	s_add_i32 m0, s53, 0xc000
	s_waitcnt lgkmcnt(0)
	ds_read_b128 v[176:179], v241
	ds_read_b128 v[192:195], v241 offset:1024
	ds_read_b128 v[172:175], v241 offset:2048
	ds_read_b128 v[188:191], v241 offset:3072
	ds_read_b128 v[168:171], v241 offset:4096
	ds_read_b128 v[184:187], v241 offset:5120
	ds_read_b128 v[164:167], v241 offset:6144
	ds_read_b128 v[180:183], v241 offset:7168
	global_load_lds_dwordx4 v[2:3], off
	v_lshl_add_u64 v[2:3], v[214:215], 0, s[28:29]
	s_add_i32 m0, s53, 0xe000
	s_nop 0
	global_load_lds_dwordx4 v[2:3], off
	s_waitcnt vmcnt(8)
	s_waitcnt lgkmcnt(0)
	s_barrier
	s_setprio 1
	s_waitcnt lgkmcnt(0)
	v_mfma_f32_16x16x32_bf16 v[128:131], v[148:151], v[176:179], v[128:131]
	v_mfma_f32_16x16x32_bf16 v[120:123], v[156:159], v[176:179], v[120:123]
	v_mfma_f32_16x16x32_bf16 v[112:115], v[148:151], v[172:175], v[112:115]
	v_mfma_f32_16x16x32_bf16 v[104:107], v[156:159], v[172:175], v[104:107]
	v_mfma_f32_16x16x32_bf16 v[96:99], v[148:151], v[168:171], v[96:99]
	v_mfma_f32_16x16x32_bf16 v[88:91], v[156:159], v[168:171], v[88:91]
	v_mfma_f32_16x16x32_bf16 v[80:83], v[148:151], v[164:167], v[80:83]
	v_mfma_f32_16x16x32_bf16 v[72:75], v[156:159], v[164:167], v[72:75]
	v_mfma_f32_16x16x32_bf16 v[128:131], v[152:155], v[192:195], v[128:131]
	v_mfma_f32_16x16x32_bf16 v[120:123], v[160:163], v[192:195], v[120:123]
	v_mfma_f32_16x16x32_bf16 v[112:115], v[152:155], v[188:191], v[112:115]
	v_mfma_f32_16x16x32_bf16 v[104:107], v[160:163], v[188:191], v[104:107]
	v_mfma_f32_16x16x32_bf16 v[96:99], v[152:155], v[184:187], v[96:99]
	v_mfma_f32_16x16x32_bf16 v[88:91], v[160:163], v[184:187], v[88:91]
	v_mfma_f32_16x16x32_bf16 v[80:83], v[152:155], v[180:183], v[80:83]
	v_mfma_f32_16x16x32_bf16 v[72:75], v[160:163], v[180:183], v[72:75]
	s_setprio 0
	s_setprio 1
	v_mfma_f32_16x16x32_bf16 v[124:127], v[132:135], v[176:179], v[124:127]
	v_mfma_f32_16x16x32_bf16 v[116:119], v[140:143], v[176:179], v[116:119]
	v_mfma_f32_16x16x32_bf16 v[108:111], v[132:135], v[172:175], v[108:111]
	v_mfma_f32_16x16x32_bf16 v[100:103], v[140:143], v[172:175], v[100:103]
	v_mfma_f32_16x16x32_bf16 v[92:95], v[132:135], v[168:171], v[92:95]
	v_mfma_f32_16x16x32_bf16 v[84:87], v[140:143], v[168:171], v[84:87]
	v_mfma_f32_16x16x32_bf16 v[76:79], v[132:135], v[164:167], v[76:79]
	v_mfma_f32_16x16x32_bf16 v[68:71], v[140:143], v[164:167], v[68:71]
	v_mfma_f32_16x16x32_bf16 v[124:127], v[136:139], v[192:195], v[124:127]
	v_mfma_f32_16x16x32_bf16 v[116:119], v[144:147], v[192:195], v[116:119]
	v_mfma_f32_16x16x32_bf16 v[108:111], v[136:139], v[188:191], v[108:111]
	v_mfma_f32_16x16x32_bf16 v[100:103], v[144:147], v[188:191], v[100:103]
	v_mfma_f32_16x16x32_bf16 v[92:95], v[136:139], v[184:187], v[92:95]
	v_mfma_f32_16x16x32_bf16 v[84:87], v[144:147], v[184:187], v[84:87]
	v_mfma_f32_16x16x32_bf16 v[76:79], v[136:139], v[180:183], v[76:79]
	v_mfma_f32_16x16x32_bf16 v[68:71], v[144:147], v[180:183], v[68:71]
	s_setprio 0
	s_barrier
	s_andn2_b64 s[6:7], exec, s[30:31]
	s_andn2_b64 vcc, exec, s[30:31]
	s_cbranch_vccnz .LBB0_449
	ds_read_b128 v[176:179], v241 offset:16384
	ds_read_b128 v[192:195], v241 offset:17408
	ds_read_b128 v[172:175], v241 offset:18432
	ds_read_b128 v[188:191], v241 offset:19456
	ds_read_b128 v[168:171], v241 offset:20480
	ds_read_b128 v[184:187], v241 offset:21504
	ds_read_b128 v[164:167], v241 offset:22528
	ds_read_b128 v[180:183], v241 offset:23552

.LBB0_624:
	s_nop 0
	s_andn2_b64 s[6:7], exec, s[8:9]
	s_andn2_b64 vcc, exec, s[8:9]
	s_mov_b64 s[20:21], s[10:11]
	s_cbranch_vccnz .LBB0_626
	s_mul_i32 s8, s59, 0x210000
	s_mul_hi_i32 s0, s59, 0x210000
	s_add_u32 s20, s2, s8
	s_addc_u32 s21, s26, s0

.LBB0_773:
	v_add_u32_e32 v0, s15, v241
	ds_read_b128 v[148:151], v0
	ds_read_b128 v[152:155], v0 offset:1024
	ds_read_b128 v[156:159], v0 offset:2048
	ds_read_b128 v[160:163], v0 offset:3072
	v_add_u32_e32 v0, s54, v241
	ds_read_b128 v[132:135], v0
	ds_read_b128 v[136:139], v0 offset:1024
	ds_read_b128 v[140:143], v0 offset:2048
	ds_read_b128 v[144:147], v0 offset:3072
	v_lshl_add_u64 v[2:3], v[218:219], 0, s[34:35]
	s_add_i32 m0, s57, 0xc000
	s_waitcnt lgkmcnt(0)
	ds_read_b128 v[176:179], v243
	ds_read_b128 v[192:195], v243 offset:1024
	ds_read_b128 v[172:175], v243 offset:2048
	ds_read_b128 v[188:191], v243 offset:3072
	ds_read_b128 v[168:171], v243 offset:4096
	ds_read_b128 v[184:187], v243 offset:5120
	ds_read_b128 v[164:167], v243 offset:6144
	ds_read_b128 v[180:183], v243 offset:7168
	global_load_lds_dwordx4 v[2:3], off
	v_lshl_add_u64 v[2:3], v[216:217], 0, s[34:35]
	s_add_i32 m0, s57, 0xe000
	s_nop 0
	global_load_lds_dwordx4 v[2:3], off
	s_waitcnt vmcnt(8)
	s_waitcnt lgkmcnt(0)
	s_barrier
	s_setprio 1
	s_waitcnt lgkmcnt(0)
	v_mfma_f32_16x16x32_bf16 v[128:131], v[148:151], v[176:179], v[128:131]
	v_mfma_f32_16x16x32_bf16 v[124:127], v[156:159], v[176:179], v[124:127]
	v_mfma_f32_16x16x32_bf16 v[120:123], v[148:151], v[172:175], v[120:123]
	v_mfma_f32_16x16x32_bf16 v[112:115], v[156:159], v[172:175], v[112:115]
	v_mfma_f32_16x16x32_bf16 v[104:107], v[148:151], v[168:171], v[104:107]
	v_mfma_f32_16x16x32_bf16 v[96:99], v[156:159], v[168:171], v[96:99]
	v_mfma_f32_16x16x32_bf16 v[88:91], v[148:151], v[164:167], v[88:91]
	v_mfma_f32_16x16x32_bf16 v[80:83], v[156:159], v[164:167], v[80:83]
	v_mfma_f32_16x16x32_bf16 v[128:131], v[152:155], v[192:195], v[128:131]
	v_mfma_f32_16x16x32_bf16 v[124:127], v[160:163], v[192:195], v[124:127]
	v_mfma_f32_16x16x32_bf16 v[120:123], v[152:155], v[188:191], v[120:123]
	v_mfma_f32_16x16x32_bf16 v[112:115], v[160:163], v[188:191], v[112:115]
	v_mfma_f32_16x16x32_bf16 v[104:107], v[152:155], v[184:187], v[104:107]
	v_mfma_f32_16x16x32_bf16 v[96:99], v[160:163], v[184:187], v[96:99]
	v_mfma_f32_16x16x32_bf16 v[88:91], v[152:155], v[180:183], v[88:91]
	v_mfma_f32_16x16x32_bf16 v[80:83], v[160:163], v[180:183], v[80:83]
	s_setprio 0
	s_setprio 1
	v_mfma_f32_16x16x32_bf16 v[116:119], v[132:135], v[176:179], v[116:119]
	v_mfma_f32_16x16x32_bf16 v[108:111], v[140:143], v[176:179], v[108:111]
	v_mfma_f32_16x16x32_bf16 v[100:103], v[132:135], v[172:175], v[100:103]
	v_mfma_f32_16x16x32_bf16 v[92:95], v[140:143], v[172:175], v[92:95]
	v_mfma_f32_16x16x32_bf16 v[84:87], v[132:135], v[168:171], v[84:87]
	v_mfma_f32_16x16x32_bf16 v[76:79], v[140:143], v[168:171], v[76:79]
	v_mfma_f32_16x16x32_bf16 v[72:75], v[132:135], v[164:167], v[72:75]
	v_mfma_f32_16x16x32_bf16 v[68:71], v[140:143], v[164:167], v[68:71]
	v_mfma_f32_16x16x32_bf16 v[116:119], v[136:139], v[192:195], v[116:119]
	v_mfma_f32_16x16x32_bf16 v[108:111], v[144:147], v[192:195], v[108:111]
	v_mfma_f32_16x16x32_bf16 v[100:103], v[136:139], v[188:191], v[100:103]
	v_mfma_f32_16x16x32_bf16 v[92:95], v[144:147], v[188:191], v[92:95]
	v_mfma_f32_16x16x32_bf16 v[84:87], v[136:139], v[184:187], v[84:87]
	v_mfma_f32_16x16x32_bf16 v[76:79], v[144:147], v[184:187], v[76:79]
	v_mfma_f32_16x16x32_bf16 v[72:75], v[136:139], v[180:183], v[72:75]
	v_mfma_f32_16x16x32_bf16 v[68:71], v[144:147], v[180:183], v[68:71]
	s_setprio 0
	s_barrier
	s_andn2_b64 s[6:7], exec, s[36:37]
	s_andn2_b64 vcc, exec, s[36:37]
	s_cbranch_vccnz .LBB0_775
	ds_read_b128 v[176:179], v243 offset:16384
	ds_read_b128 v[192:195], v243 offset:17408
	ds_read_b128 v[172:175], v243 offset:18432
	ds_read_b128 v[188:191], v243 offset:19456
	ds_read_b128 v[168:171], v243 offset:20480
	ds_read_b128 v[184:187], v243 offset:21504
	ds_read_b128 v[164:167], v243 offset:22528
	ds_read_b128 v[180:183], v243 offset:23552

.Latt_A_steady:
	s_waitcnt vmcnt(4)

.LBB0_1331:
	s_add_i32 s34, s72, 1
	s_cmp_lg_u32 s72, 4
	s_cselect_b32 s34, s34, 0
	s_add_i32 s35, s37, 1
	s_cmp_lg_u32 s37, 4
	s_cselect_b32 s37, s35, 0
	s_addk_i32 s36, 0x4000
	s_add_i32 s77, s77, 1
	s_add_i32 s50, s73, -2
	v_lshl_add_u64 v[114:115], v[114:115], 0, s[74:75]
	v_lshl_add_u64 v[116:117], v[116:117], 0, s[44:45]
	s_cmp_eq_u32 s50, s71
	v_lshl_add_u64 v[118:119], v[118:119], 0, s[44:45]
	s_cbranch_scc1 .Latt_exitA
	s_mov_b32 s49, s72
	s_lshl_b32 s51, s49, 14
	v_add_u32_e32 v131, s51, v124
	ds_read_b128 v[204:207], v131 offset:49152
	ds_read_b128 v[208:211], v131 offset:51200
	ds_read_b128 v[212:215], v131 offset:53248
	ds_read_b128 v[216:219], v131 offset:55296
	s_mov_b32 s72, s34
	s_cmp_ge_u32 s50, s0
	s_mov_b64 s[34:35], -1
	s_cbranch_scc0 .Latt_B_steady

.Latt_B_1331:
	s_add_i32 s34, s72, 1
	s_cmp_lg_u32 s72, 4
	s_cselect_b32 s34, s34, 0
	s_add_i32 s35, s37, 1
	s_cmp_lg_u32 s37, 4
	s_cselect_b32 s37, s35, 0
	s_addk_i32 s36, 0x4000
	s_add_i32 s77, s77, 1
	s_add_i32 s50, s73, -2
	v_lshl_add_u64 v[114:115], v[114:115], 0, s[74:75]
	v_lshl_add_u64 v[116:117], v[116:117], 0, s[44:45]
	s_cmp_eq_u32 s50, s71
	v_lshl_add_u64 v[118:119], v[118:119], 0, s[44:45]
	s_cbranch_scc1 .LBB0_1333
	s_mov_b32 s49, s72
	s_lshl_b32 s51, s49, 14
	v_add_u32_e32 v131, s51, v124
	ds_read_b128 v[204:207], v131 offset:49152
	ds_read_b128 v[208:211], v131 offset:51200
	ds_read_b128 v[212:215], v131 offset:53248
	ds_read_b128 v[216:219], v131 offset:55296
	s_mov_b32 s72, s34
	s_cmp_ge_u32 s50, s0
	s_mov_b64 s[34:35], -1
	s_cbranch_scc0 .Latt_A_steady
	s_branch .LBB0_1321

.LBB0_1465:
	s_nop 0
	s_andn2_b64 s[6:7], exec, s[8:9]
	s_andn2_b64 vcc, exec, s[8:9]
	s_mov_b64 s[18:19], s[10:11]
	s_cbranch_vccnz .LBB0_1467
	s_mul_i32 s17, s58, 0xc0000
	s_mul_hi_i32 s0, s58, 0xc0000
	s_add_u32 s18, s2, s17
	s_addc_u32 s19, s24, s0

.LBB0_1609:
	v_add_u32_e32 v0, s23, v225
	ds_read_b128 v[148:151], v0
	ds_read_b128 v[152:155], v0 offset:1024
	ds_read_b128 v[156:159], v0 offset:2048
	ds_read_b128 v[160:163], v0 offset:3072
	v_add_u32_e32 v0, s50, v225
	ds_read_b128 v[132:135], v0
	ds_read_b128 v[136:139], v0 offset:1024
	ds_read_b128 v[140:143], v0 offset:2048
	ds_read_b128 v[144:147], v0 offset:3072
	v_lshl_add_u64 v[2:3], v[216:217], 0, s[28:29]
	s_add_i32 m0, s53, 0xc000
	s_waitcnt lgkmcnt(0)
	ds_read_b128 v[176:179], v241
	ds_read_b128 v[192:195], v241 offset:1024
	ds_read_b128 v[172:175], v241 offset:2048
	ds_read_b128 v[188:191], v241 offset:3072
	ds_read_b128 v[168:171], v241 offset:4096
	ds_read_b128 v[184:187], v241 offset:5120
	ds_read_b128 v[164:167], v241 offset:6144
	ds_read_b128 v[180:183], v241 offset:7168
	global_load_lds_dwordx4 v[2:3], off
	v_lshl_add_u64 v[2:3], v[214:215], 0, s[28:29]
	s_add_i32 m0, s53, 0xe000
	s_nop 0
	global_load_lds_dwordx4 v[2:3], off
	s_waitcnt vmcnt(8)
	s_waitcnt lgkmcnt(0)
	s_barrier
	s_setprio 1
	s_waitcnt lgkmcnt(0)
	v_mfma_f32_16x16x32_bf16 v[128:131], v[148:151], v[176:179], v[128:131]
	v_mfma_f32_16x16x32_bf16 v[120:123], v[156:159], v[176:179], v[120:123]
	v_mfma_f32_16x16x32_bf16 v[112:115], v[148:151], v[172:175], v[112:115]
	v_mfma_f32_16x16x32_bf16 v[104:107], v[156:159], v[172:175], v[104:107]
	v_mfma_f32_16x16x32_bf16 v[96:99], v[148:151], v[168:171], v[96:99]
	v_mfma_f32_16x16x32_bf16 v[88:91], v[156:159], v[168:171], v[88:91]
	v_mfma_f32_16x16x32_bf16 v[80:83], v[148:151], v[164:167], v[80:83]
	v_mfma_f32_16x16x32_bf16 v[72:75], v[156:159], v[164:167], v[72:75]
	v_mfma_f32_16x16x32_bf16 v[128:131], v[152:155], v[192:195], v[128:131]
	v_mfma_f32_16x16x32_bf16 v[120:123], v[160:163], v[192:195], v[120:123]
	v_mfma_f32_16x16x32_bf16 v[112:115], v[152:155], v[188:191], v[112:115]
	v_mfma_f32_16x16x32_bf16 v[104:107], v[160:163], v[188:191], v[104:107]
	v_mfma_f32_16x16x32_bf16 v[96:99], v[152:155], v[184:187], v[96:99]
	v_mfma_f32_16x16x32_bf16 v[88:91], v[160:163], v[184:187], v[88:91]
	v_mfma_f32_16x16x32_bf16 v[80:83], v[152:155], v[180:183], v[80:83]
	v_mfma_f32_16x16x32_bf16 v[72:75], v[160:163], v[180:183], v[72:75]
	s_setprio 0
	s_setprio 1
	v_mfma_f32_16x16x32_bf16 v[124:127], v[132:135], v[176:179], v[124:127]
	v_mfma_f32_16x16x32_bf16 v[116:119], v[140:143], v[176:179], v[116:119]
	v_mfma_f32_16x16x32_bf16 v[108:111], v[132:135], v[172:175], v[108:111]
	v_mfma_f32_16x16x32_bf16 v[100:103], v[140:143], v[172:175], v[100:103]
	v_mfma_f32_16x16x32_bf16 v[92:95], v[132:135], v[168:171], v[92:95]
	v_mfma_f32_16x16x32_bf16 v[84:87], v[140:143], v[168:171], v[84:87]
	v_mfma_f32_16x16x32_bf16 v[76:79], v[132:135], v[164:167], v[76:79]
	v_mfma_f32_16x16x32_bf16 v[68:71], v[140:143], v[164:167], v[68:71]
	v_mfma_f32_16x16x32_bf16 v[124:127], v[136:139], v[192:195], v[124:127]
	v_mfma_f32_16x16x32_bf16 v[116:119], v[144:147], v[192:195], v[116:119]
	v_mfma_f32_16x16x32_bf16 v[108:111], v[136:139], v[188:191], v[108:111]
	v_mfma_f32_16x16x32_bf16 v[100:103], v[144:147], v[188:191], v[100:103]
	v_mfma_f32_16x16x32_bf16 v[92:95], v[136:139], v[184:187], v[92:95]
	v_mfma_f32_16x16x32_bf16 v[84:87], v[144:147], v[184:187], v[84:87]
	v_mfma_f32_16x16x32_bf16 v[76:79], v[136:139], v[180:183], v[76:79]
	v_mfma_f32_16x16x32_bf16 v[68:71], v[144:147], v[180:183], v[68:71]
	s_setprio 0
	s_barrier
	s_andn2_b64 s[4:5], exec, s[30:31]
	s_andn2_b64 vcc, exec, s[30:31]
	s_cbranch_vccnz .LBB0_1611
	ds_read_b128 v[176:179], v241 offset:16384
	ds_read_b128 v[192:195], v241 offset:17408
	ds_read_b128 v[172:175], v241 offset:18432
	ds_read_b128 v[188:191], v241 offset:19456
	ds_read_b128 v[168:171], v241 offset:20480
	ds_read_b128 v[184:187], v241 offset:21504
	ds_read_b128 v[164:167], v241 offset:22528
	ds_read_b128 v[180:183], v241 offset:23552

.LBB0_1788:
	s_nop 0
	s_andn2_b64 s[6:7], exec, s[4:5]
	s_andn2_b64 vcc, exec, s[4:5]
	s_mov_b64 s[16:17], s[8:9]
	s_cbranch_vccnz .LBB0_1790
	s_mul_i32 s4, s57, 0x210000
	s_mul_hi_i32 s0, s57, 0x210000
	s_add_u32 s16, s2, s4
	s_addc_u32 s17, s22, s0
